# GLA chunk loop waitcnt placement: v/g_low prefetch issued right after LDS staging, q/k prefetch waited at first consumer with counted waits (was one vmcnt(0) at loop top)
# speedup vs baseline: 1.0015x; 1.0015x over previous
; #define LAS __attribute__((address_space(3)))
; DI void gla_item(ldsp lds, const Params& p, const bf16_t* proj, bf16_t* obuf, const float* q0k0, int jl, int item, int tid, int wid, int lane) {
;     ...
;     for (int n = 0; n < 32; ++n) {
;         const size_t rowb = (size_t)b * 2048 + n * 64;
;         *(LAS u32x4*)(Vl + row0 * S96 + ch0 * 16) = vreg0;
;         if (has1) *(LAS u32x4*)(Vl + row1 * S96 + ch1 * 16) = vreg1;
;         if (tid < 128) *(LAS u32x4*)(GL + (tid >> 1) * SGL + (tid & 1) * 16) = greg;
;         __syncthreads();
.LBB0_484:
	s_cmp_eq_u32 s0, 0
	s_cbranch_scc1 .Lgla_tw0
	s_cmp_lg_u64 s[46:47], 0
	s_cbranch_scc1 .Lgla_tw4
	s_waitcnt vmcnt(2)
	s_branch .Lgla_twd
.Lgla_tw4:
	s_waitcnt vmcnt(4)
	s_branch .Lgla_twd

; #define LAS __attribute__((address_space(3)))
; DI void gla_item(ldsp lds, const Params& p, const bf16_t* proj, bf16_t* obuf, const float* q0k0, int jl, int item, int tid, int wid, int lane) {
;     ...
;         *(LAS u32x4*)(Vl + row0 * S96 + ch0 * 16) = vreg0;
;         if (has1) *(LAS u32x4*)(Vl + row1 * S96 + ch1 * 16) = vreg1;
;         if (tid < 128) *(LAS u32x4*)(GL + (tid >> 1) * SGL + (tid & 1) * 16) = greg;
;         __syncthreads();
.Lgla_twd:
	ds_write_b128 v178, v[8:11]
	s_and_saveexec_b64 s[22:23], s[46:47]
	ds_write_b128 v179, v[24:27]
	s_or_b64 exec, exec, s[22:23]
	s_and_saveexec_b64 s[22:23], s[48:49]
	ds_write_b128 v198, v[28:31]
	s_or_b64 exec, exec, s[22:23]
	v_cndmask_b32_e64 v13, 0, 1, s[36:37]
	v_cmp_ne_u32_e64 s[74:75], 1, v13
	s_andn2_b64 vcc, exec, s[36:37]
	s_waitcnt lgkmcnt(0)
	s_barrier
	s_cmp_eq_u32 s0, 31
	s_cbranch_scc1 .Lgla_nov
	v_lshl_add_u64 v[8:9], v[134:135], 0, v[132:133]
	global_load_dwordx4 v[8:11], v[8:9], off
	s_and_saveexec_b64 s[22:23], s[46:47]
	s_cbranch_execz .Lgla_nov1
	v_lshl_add_u64 v[14:15], v[126:127], 0, v[124:125]
	global_load_dwordx4 v[24:27], v[14:15], off

; DI f32x4 mfma16(bf16x8 a, bf16x8 b, f32x4 c) { return __builtin_amdgcn_mfma_f32_16x16x32_bf16(a, b, c, 0, 0, 0); }
; DI float logsig_f(float x) { return fminf(x, 0.f) - __logf(1.0f + __expf(-fabsf(x))); }
; DI void gla_item(ldsp lds, const Params& p, const bf16_t* proj, bf16_t* obuf, const float* q0k0, int jl, int item, int tid, int wid, int lane) {
;     ...
;         if (wid < 6) {
;             const int d = 16 * wid + li; const float bias = BG[d];
;             const bf16x8 bb = lds_rd8(WG + (16 * wid + li) * SGL + quad * 16);
;             float base = 0.f;
; #pragma unroll
;             for (int it = 0; it < 4; ++it) {
;                 const bf16x8 a = lds_rd8(GL + (16 * it + li) * SGL + quad * 16);
;                 const f32x4 c = mfma16(a, bb, (f32x4){0.f, 0.f, 0.f, 0.f});
;                 const float c0 = logsig_f(c[0] + bias) * (1.0f / 16.0f);
;                 const float c1 = c0 + logsig_f(c[1] + bias) * (1.0f / 16.0f);
;                 const float c2 = c1 + logsig_f(c[2] + bias) * (1.0f / 16.0f);
;                 const float c3 = c2 + logsig_f(c[3] + bias) * (1.0f / 16.0f);
;                 float sc = c3;
.Lgla_nov:
	s_cbranch_vccnz .LBB0_490
	v_add_u32_e32 v14, v94, v69
	ds_read_b32 v13, v92 offset:12800
	ds_read_b128 v[60:63], v14 offset:5120
	ds_read_b128 v[64:67], v180
	ds_read_b128 v[200:203], v180 offset:1280
	ds_read_b128 v[204:207], v180 offset:2560
	ds_read_b128 v[208:211], v182
	s_waitcnt lgkmcnt(0)
	v_mfma_f32_16x16x32_bf16 v[64:67], v[64:67], v[60:63], 0
	v_mfma_f32_16x16x32_bf16 v[200:203], v[200:203], v[60:63], 0
	v_mfma_f32_16x16x32_bf16 v[204:207], v[204:207], v[60:63], 0
	v_mfma_f32_16x16x32_bf16 v[208:211], v[208:211], v[60:63], 0
	s_nop 4
	v_add_f32_e32 v64, v13, v64
	v_add_f32_e32 v65, v13, v65
	v_add_f32_e32 v66, v13, v66
	v_add_f32_e32 v67, v13, v67
	v_add_f32_e32 v200, v13, v200
	v_add_f32_e32 v201, v13, v201
	v_add_f32_e32 v202, v13, v202
	v_add_f32_e32 v203, v13, v203
	v_min_f32_e32 v212, 0, v64
	v_min_f32_e32 v213, 0, v65
	v_min_f32_e32 v214, 0, v66
	v_min_f32_e32 v215, 0, v67
	v_min_f32_e32 v216, 0, v200
	v_min_f32_e32 v217, 0, v201
	v_min_f32_e32 v218, 0, v202
	v_min_f32_e32 v219, 0, v203
	v_mul_f32_e64 v64, |v64|, s89
	v_mul_f32_e64 v65, |v65|, s89
	v_mul_f32_e64 v66, |v66|, s89
	v_mul_f32_e64 v67, |v67|, s89
	v_mul_f32_e64 v200, |v200|, s89
	v_mul_f32_e64 v201, |v201|, s89
	v_mul_f32_e64 v202, |v202|, s89
	v_mul_f32_e64 v203, |v203|, s89
	v_exp_f32_e32 v64, v64
	v_exp_f32_e32 v65, v65
	v_exp_f32_e32 v66, v66
	v_exp_f32_e32 v67, v67
	v_exp_f32_e32 v200, v200
	v_exp_f32_e32 v201, v201
	v_exp_f32_e32 v202, v202
	v_exp_f32_e32 v203, v203
	v_add_f32_e32 v64, 1.0, v64
	v_add_f32_e32 v65, 1.0, v65
	v_add_f32_e32 v66, 1.0, v66
	v_add_f32_e32 v67, 1.0, v67
	v_add_f32_e32 v200, 1.0, v200
	v_add_f32_e32 v201, 1.0, v201
	v_add_f32_e32 v202, 1.0, v202
	v_add_f32_e32 v203, 1.0, v203
	v_log_f32_e32 v64, v64
	v_log_f32_e32 v65, v65
	v_log_f32_e32 v66, v66
	v_log_f32_e32 v67, v67
	v_log_f32_e32 v200, v200
	v_log_f32_e32 v201, v201
	v_log_f32_e32 v202, v202
	v_log_f32_e32 v203, v203
	v_mul_f32_e32 v220, 0x3f317217, v64
	v_mul_f32_e32 v221, 0x3f317217, v65
	v_mul_f32_e32 v222, 0x3f317217, v66
	v_mul_f32_e32 v223, 0x3f317217, v67
	v_mul_f32_e32 v224, 0x3f317217, v200
	v_mul_f32_e32 v225, 0x3f317217, v201
	v_mul_f32_e32 v226, 0x3f317217, v202
	v_mul_f32_e32 v227, 0x3f317217, v203
	v_fma_f32 v220, v64, s84, -v220
	v_fma_f32 v221, v65, s84, -v221
	v_fma_f32 v222, v66, s84, -v222
	v_fma_f32 v223, v67, s84, -v223
	v_fma_f32 v224, v200, s84, -v224
	v_fma_f32 v225, v201, s84, -v225
	v_fma_f32 v226, v202, s84, -v226
	v_fma_f32 v227, v203, s84, -v227
	v_fmac_f32_e32 v220, 0x3377d1cf, v64
	v_fmac_f32_e32 v221, 0x3377d1cf, v65
	v_fmac_f32_e32 v222, 0x3377d1cf, v66
	v_fmac_f32_e32 v223, 0x3377d1cf, v67
	v_fmac_f32_e32 v224, 0x3377d1cf, v200
	v_fmac_f32_e32 v225, 0x3377d1cf, v201
	v_fmac_f32_e32 v226, 0x3377d1cf, v202
	v_fmac_f32_e32 v227, 0x3377d1cf, v203
	v_fmac_f32_e32 v220, 0x3f317217, v64
	v_fmac_f32_e32 v221, 0x3f317217, v65
	v_fmac_f32_e32 v222, 0x3f317217, v66
	v_fmac_f32_e32 v223, 0x3f317217, v67
	v_fmac_f32_e32 v224, 0x3f317217, v200
	v_fmac_f32_e32 v225, 0x3f317217, v201
	v_fmac_f32_e32 v226, 0x3f317217, v202
	v_fmac_f32_e32 v227, 0x3f317217, v203
	v_sub_f32_e32 v64, v212, v220
	v_sub_f32_e32 v65, v213, v221
	v_sub_f32_e32 v66, v214, v222
	v_sub_f32_e32 v67, v215, v223
	v_sub_f32_e32 v200, v216, v224
	v_sub_f32_e32 v201, v217, v225
	v_sub_f32_e32 v202, v218, v226
	v_sub_f32_e32 v203, v219, v227
	v_add_f32_e32 v204, v13, v204
	v_add_f32_e32 v205, v13, v205
	v_add_f32_e32 v206, v13, v206
	v_add_f32_e32 v207, v13, v207
	v_add_f32_e32 v208, v13, v208
	v_add_f32_e32 v209, v13, v209
	v_add_f32_e32 v210, v13, v210
	v_add_f32_e32 v211, v13, v211
	v_min_f32_e32 v212, 0, v204
	v_min_f32_e32 v213, 0, v205
	v_min_f32_e32 v214, 0, v206
	v_min_f32_e32 v215, 0, v207
	v_min_f32_e32 v216, 0, v208
	v_min_f32_e32 v217, 0, v209
	v_min_f32_e32 v218, 0, v210
	v_min_f32_e32 v219, 0, v211
	v_mul_f32_e64 v204, |v204|, s89
	v_mul_f32_e64 v205, |v205|, s89
	v_mul_f32_e64 v206, |v206|, s89
	v_mul_f32_e64 v207, |v207|, s89
	v_mul_f32_e64 v208, |v208|, s89
	v_mul_f32_e64 v209, |v209|, s89
	v_mul_f32_e64 v210, |v210|, s89
	v_mul_f32_e64 v211, |v211|, s89
	v_exp_f32_e32 v204, v204
	v_exp_f32_e32 v205, v205
	v_exp_f32_e32 v206, v206
	v_exp_f32_e32 v207, v207
	v_exp_f32_e32 v208, v208
	v_exp_f32_e32 v209, v209
	v_exp_f32_e32 v210, v210
	v_exp_f32_e32 v211, v211
	v_add_f32_e32 v204, 1.0, v204
	v_add_f32_e32 v205, 1.0, v205
	v_add_f32_e32 v206, 1.0, v206
	v_add_f32_e32 v207, 1.0, v207
	v_add_f32_e32 v208, 1.0, v208
	v_add_f32_e32 v209, 1.0, v209
	v_add_f32_e32 v210, 1.0, v210
	v_add_f32_e32 v211, 1.0, v211
	v_log_f32_e32 v204, v204
	v_log_f32_e32 v205, v205
	v_log_f32_e32 v206, v206
	v_log_f32_e32 v207, v207
	v_log_f32_e32 v208, v208
	v_log_f32_e32 v209, v209
	v_log_f32_e32 v210, v210
	v_log_f32_e32 v211, v211
	v_mul_f32_e32 v220, 0x3f317217, v204
	v_mul_f32_e32 v221, 0x3f317217, v205
	v_mul_f32_e32 v222, 0x3f317217, v206
	v_mul_f32_e32 v223, 0x3f317217, v207
	v_mul_f32_e32 v224, 0x3f317217, v208
	v_mul_f32_e32 v225, 0x3f317217, v209
	v_mul_f32_e32 v226, 0x3f317217, v210
	v_mul_f32_e32 v227, 0x3f317217, v211
	v_fma_f32 v220, v204, s84, -v220
	v_fma_f32 v221, v205, s84, -v221
	v_fma_f32 v222, v206, s84, -v222
	v_fma_f32 v223, v207, s84, -v223
	v_fma_f32 v224, v208, s84, -v224
	v_fma_f32 v225, v209, s84, -v225
	v_fma_f32 v226, v210, s84, -v226
	v_fma_f32 v227, v211, s84, -v227
	v_fmac_f32_e32 v220, 0x3377d1cf, v204
	v_fmac_f32_e32 v221, 0x3377d1cf, v205
	v_fmac_f32_e32 v222, 0x3377d1cf, v206
	v_fmac_f32_e32 v223, 0x3377d1cf, v207
	v_fmac_f32_e32 v224, 0x3377d1cf, v208
	v_fmac_f32_e32 v225, 0x3377d1cf, v209
	v_fmac_f32_e32 v226, 0x3377d1cf, v210
	v_fmac_f32_e32 v227, 0x3377d1cf, v211
	v_fmac_f32_e32 v220, 0x3f317217, v204
	v_fmac_f32_e32 v221, 0x3f317217, v205
	v_fmac_f32_e32 v222, 0x3f317217, v206
	v_fmac_f32_e32 v223, 0x3f317217, v207
	v_fmac_f32_e32 v224, 0x3f317217, v208
	v_fmac_f32_e32 v225, 0x3f317217, v209
	v_fmac_f32_e32 v226, 0x3f317217, v210
	v_fmac_f32_e32 v227, 0x3f317217, v211
	v_sub_f32_e32 v204, v212, v220
	v_sub_f32_e32 v205, v213, v221
	v_sub_f32_e32 v206, v214, v222
	v_sub_f32_e32 v207, v215, v223
	v_sub_f32_e32 v208, v216, v224
	v_sub_f32_e32 v209, v217, v225
	v_sub_f32_e32 v210, v218, v226
	v_sub_f32_e32 v211, v219, v227
	v_mul_f32_e32 v212, 0x3d800000, v65
	v_mul_f32_e32 v213, 0x3d800000, v201
	v_mul_f32_e32 v214, 0x3d800000, v205
	v_mul_f32_e32 v215, 0x3d800000, v209
	v_fmac_f32_e32 v212, 0x3d800000, v64
	v_fmac_f32_e32 v213, 0x3d800000, v200
	v_fmac_f32_e32 v214, 0x3d800000, v204
	v_fmac_f32_e32 v215, 0x3d800000, v208
	v_fmamk_f32 v216, v66, 0x3d800000, v212
	v_fmamk_f32 v217, v202, 0x3d800000, v213
	v_fmamk_f32 v218, v206, 0x3d800000, v214
	v_fmamk_f32 v219, v210, 0x3d800000, v215
	v_fmamk_f32 v220, v67, 0x3d800000, v216
	v_fmamk_f32 v221, v203, 0x3d800000, v217
	v_fmamk_f32 v222, v207, 0x3d800000, v218
	v_fmamk_f32 v223, v211, 0x3d800000, v219
	ds_bpermute_b32 v224, v95, v220
	ds_bpermute_b32 v225, v95, v221
	ds_bpermute_b32 v226, v95, v222
	ds_bpermute_b32 v227, v95, v223
	s_waitcnt lgkmcnt(0)
; #define LAS __attribute__((address_space(3)))
; DI unsigned cvt_pk_bf16(float lo, float hi) { const f32x2_t v = {lo, hi}; const bf16v2_t b = __builtin_convertvector(v, bf16v2_t); return __builtin_bit_cast(unsigned, b); }
; DI void gla_item(ldsp lds, const Params& p, const bf16_t* proj, bf16_t* obuf, const float* q0k0, int jl, int item, int tid, int wid, int lane) {
;     ...
;                 float t = __shfl_up(sc, 16); if (quad >= 1) sc += t;
;                 t = __shfl_up(sc, 32); if (quad >= 2) sc += t;
;                 const float tot = __shfl(sc, 48 + li);
;                 const float o = base + (sc - c3);
;                 LAS float* lp = LA + (16 * it + quad * 4) * SLA + d;
;                 lp[0] = o + c0; lp[SLA] = o + c1; lp[2 * SLA] = o + c2; lp[3 * SLA] = o + c3;
;                 base += tot;
;             }
; #pragma unroll
;             for (int dt = 0; dt < 6; ++dt) { u32x2 w; w.x = cvt_pk_bf16(S[dt][0], S[dt][1]); w.y = cvt_pk_bf16(S[dt][2], S[dt][3]);
;                 *(LAS u32x2*)(ST + (16 * wid + li) * S96 + (16 * dt + quad * 4) * 2) = w; }
;         }
;         __syncthreads();
; #pragma unroll
;         for (int cc = 0; cc < 2; ++cc) {
;             if (cc == 1 && !has1) break;
;             const int row = cc ? row1 : row0, ch = cc ? ch1 : ch0;
;             const u32x4 qv = cc ? qreg1 : qreg0, kv = cc ? kreg1 : kreg0;
;             const f32x4 b0v = *(LAS f32x4*)(LA + row * SLA + ch * 8), b1v = *(LAS f32x4*)(LA + row * SLA + ch * 8 + 4);
;             const f32x4 l0v = *(LAS f32x4*)(LA + 63 * SLA + ch * 8), l1v = *(LAS f32x4*)(LA + 63 * SLA + ch * 8 + 4);
	v_add_f32_e32 v224, v220, v224
	v_add_f32_e32 v225, v221, v225
	v_add_f32_e32 v226, v222, v226
	v_add_f32_e32 v227, v223, v227
	v_cndmask_b32_e64 v228, v224, v220, s[50:51]
	v_cndmask_b32_e64 v229, v225, v221, s[50:51]
	v_cndmask_b32_e64 v230, v226, v222, s[50:51]
	v_cndmask_b32_e64 v232, v227, v223, s[50:51]
	ds_bpermute_b32 v224, v163, v228
	ds_bpermute_b32 v225, v163, v229
	ds_bpermute_b32 v226, v163, v230
	ds_bpermute_b32 v227, v163, v232
	s_waitcnt lgkmcnt(0)
	v_add_f32_e32 v224, v228, v224
	v_add_f32_e32 v225, v229, v225
	v_add_f32_e32 v226, v230, v226
	v_add_f32_e32 v227, v232, v227
	v_cndmask_b32_e64 v228, v228, v224, s[52:53]
	v_cndmask_b32_e64 v229, v229, v225, s[52:53]
	v_cndmask_b32_e64 v230, v230, v226, s[52:53]
	v_cndmask_b32_e64 v232, v232, v227, s[52:53]
	ds_bpermute_b32 v224, v164, v228
	ds_bpermute_b32 v225, v164, v229
	ds_bpermute_b32 v226, v164, v230
	v_sub_f32_e32 v242, v228, v220
	v_sub_f32_e32 v243, v229, v221
	v_sub_f32_e32 v244, v230, v222
	v_sub_f32_e32 v245, v232, v223
	v_add_f32_e32 v246, 0, v242
	s_waitcnt lgkmcnt(0)
	v_add_f32_e32 v250, 0, v224
	v_add_f32_e32 v247, v250, v243
	v_add_f32_e32 v250, v250, v225
	v_add_f32_e32 v248, v250, v244
	v_add_f32_e32 v250, v250, v226
	v_add_f32_e32 v249, v250, v245
	v_add_u32_e32 v160, 0x3400, v181
	v_fmamk_f32 v14, v64, 0x3d800000, v246
	v_add_f32_e32 v15, v212, v246
	ds_write2_b32 v160, v14, v15 offset1:100
	v_add_u32_e32 v161, 0x3720, v181
	v_add_f32_e32 v158, v216, v246
	v_add_f32_e32 v159, v220, v246
	ds_write2_b32 v161, v158, v159 offset1:100
	v_add_u32_e32 v160, 0x4d00, v181
	v_fmamk_f32 v14, v200, 0x3d800000, v247
	v_add_f32_e32 v15, v213, v247
	ds_write2_b32 v160, v14, v15 offset1:100
	v_add_u32_e32 v161, 0x5020, v181
	v_add_f32_e32 v158, v217, v247
	v_add_f32_e32 v159, v221, v247
	ds_write2_b32 v161, v158, v159 offset1:100
	v_add_u32_e32 v160, 0x6600, v181
	v_fmamk_f32 v14, v204, 0x3d800000, v248
	v_add_f32_e32 v15, v214, v248
	ds_write2_b32 v160, v14, v15 offset1:100
	v_add_u32_e32 v161, 0x6920, v181
	v_add_f32_e32 v158, v218, v248
	v_add_f32_e32 v159, v222, v248
	ds_write2_b32 v161, v158, v159 offset1:100
	v_add_u32_e32 v160, 0x7f00, v181
	v_fmamk_f32 v14, v208, 0x3d800000, v249
	v_add_f32_e32 v15, v215, v249
	ds_write2_b32 v160, v14, v15 offset1:100
	v_add_u32_e32 v161, 0x8220, v181
	v_add_f32_e32 v158, v219, v249
	v_add_f32_e32 v159, v223, v249
	ds_write2_b32 v161, v158, v159 offset1:100
	v_cvt_pk_bf16_f32 v14, v40, v41
	v_cvt_pk_bf16_f32 v15, v42, v43
	v_add_u32_e32 v13, v165, v68
	v_cvt_pk_bf16_f32 v60, v52, v53
	v_cvt_pk_bf16_f32 v61, v54, v55
	ds_write2_b64 v13, v[14:15], v[60:61] offset1:4
	v_cvt_pk_bf16_f32 v14, v48, v49
	v_cvt_pk_bf16_f32 v15, v50, v51
	v_cvt_pk_bf16_f32 v60, v36, v37
	v_cvt_pk_bf16_f32 v61, v38, v39
	ds_write2_b64 v13, v[14:15], v[60:61] offset0:8 offset1:12
	v_cvt_pk_bf16_f32 v14, v44, v45
	v_cvt_pk_bf16_f32 v15, v46, v47
	v_cvt_pk_bf16_f32 v60, v56, v57
	v_cvt_pk_bf16_f32 v61, v58, v59
	ds_write2_b64 v13, v[14:15], v[60:61] offset0:16 offset1:20
.LBB0_490:
	s_waitcnt lgkmcnt(0)
	s_barrier
	ds_read_b128 v[60:63], v166 offset:13312
	ds_read_b128 v[64:67], v166 offset:13328
	ds_read_b128 v[200:203], v167 offset:38512
	ds_read_b128 v[204:207], v167 offset:38528
	s_cmp_eq_u32 s0, 31
	s_cbranch_scc1 .Lgla_dw0
	s_cmp_lg_u64 s[48:49], 0
	s_cbranch_scc1 .Lgla_dw3
	s_cmp_lg_u64 s[46:47], 0
	s_cbranch_scc1 .Lgla_dw2
	s_waitcnt vmcnt(1)
	s_branch .Lgla_dwd
.Lgla_dw2:
	s_waitcnt vmcnt(2)
	s_branch .Lgla_dwd
.Lgla_dw3:
	s_waitcnt vmcnt(3)
	s_branch .Lgla_dwd

; #define LAS __attribute__((address_space(3)))
; DI unsigned cvt_pk_bf16(float lo, float hi) { const f32x2_t v = {lo, hi}; const bf16v2_t b = __builtin_convertvector(v, bf16v2_t); return __builtin_bit_cast(unsigned, b); }
; DI float bf_lo(unsigned u) { return __uint_as_float(u << 16); }
; DI float bf_hi(unsigned u) { return __uint_as_float(u & 0xffff0000u); }
; DI void gla_item(ldsp lds, const Params& p, const bf16_t* proj, bf16_t* obuf, const float* q0k0, int jl, int item, int tid, int wid, int lane) {
;     ...
; #pragma unroll
;         for (int cc = 0; cc < 2; ++cc) {
;             if (cc == 1 && !has1) break;
;             const int row = cc ? row1 : row0, ch = cc ? ch1 : ch0;
;             const u32x4 qv = cc ? qreg1 : qreg0, kv = cc ? kreg1 : kreg0;
;             const f32x4 b0v = *(LAS f32x4*)(LA + row * SLA + ch * 8), b1v = *(LAS f32x4*)(LA + row * SLA + ch * 8 + 4);
;             const f32x4 l0v = *(LAS f32x4*)(LA + 63 * SLA + ch * 8), l1v = *(LAS f32x4*)(LA + 63 * SLA + ch * 8 + 4);
;             u32x4 qi, ki, ko;
; #pragma unroll
;             for (int e2 = 0; e2 < 4; ++e2) {
;                 const float bA = e2 < 2 ? b0v[2 * e2] : b1v[2 * e2 - 4], bB = e2 < 2 ? b0v[2 * e2 + 1] : b1v[2 * e2 - 3];
;                 const float lA = e2 < 2 ? l0v[2 * e2] : l1v[2 * e2 - 4], lB = e2 < 2 ? l0v[2 * e2 + 1] : l1v[2 * e2 - 3];
;                 const float qa = bf_lo(qv[e2]), qb = bf_hi(qv[e2]), ka = bf_lo(kv[e2]), kb = bf_hi(kv[e2]);
;                 qi[e2] = cvt_pk_bf16(qa * 0.10206207261596575f * __expf(bA), qb * 0.10206207261596575f * __expf(bB));
;                 ki[e2] = cvt_pk_bf16(ka * __expf(-bA), kb * __expf(-bB));
;                 ko[e2] = cvt_pk_bf16(ka * __expf(lA - bA), kb * __expf(lB - bB));
;             }
;             *(LAS u32x4*)(QI + row * S96 + ch * 16) = qi;
;             *(LAS u32x4*)(KI + row * S96 + ch * 16) = ki;
;             *(LAS u32x4*)(KO + row * S96 + ch * 16) = ko;
;         }
.Lgla_dwd:
	v_lshlrev_b32_e32 v158, 16, v0
	s_waitcnt lgkmcnt(3)
	v_mul_f32_e32 v13, 0x3fb8aa3b, v60
	v_exp_f32_e32 v14, v13
	v_mul_f32_e32 v13, 0x3fb8aa3b, v61
	v_exp_f32_e32 v15, v13
	v_and_b32_e32 v159, 0xffff0000, v0
	v_pk_mul_f32 v[158:159], v[158:159], s[20:21] op_sel_hi:[1,0]
	v_mul_f32_e32 v13, 0xbfb8aa3b, v60
	v_pk_mul_f32 v[14:15], v[158:159], v[14:15]
	v_lshlrev_b32_e32 v160, 16, v4
	v_cvt_pk_bf16_f32 v208, v14, v15
	v_exp_f32_e32 v14, v13
	v_mul_f32_e32 v13, 0xbfb8aa3b, v61
	v_exp_f32_e32 v15, v13
	s_waitcnt lgkmcnt(1)
	v_sub_f32_e32 v13, v200, v60
	v_mul_f32_e32 v13, 0x3fb8aa3b, v13
	v_exp_f32_e32 v158, v13
	v_sub_f32_e32 v13, v201, v61
	v_mul_f32_e32 v13, 0x3fb8aa3b, v13
	v_exp_f32_e32 v159, v13
	v_and_b32_e32 v161, 0xffff0000, v4
	v_pk_mul_f32 v[14:15], v[14:15], v[160:161]
	v_mul_f32_e32 v13, 0x3fb8aa3b, v62
	v_cvt_pk_bf16_f32 v60, v14, v15
	v_pk_mul_f32 v[14:15], v[158:159], v[160:161]
	v_lshlrev_b32_e32 v158, 16, v1
	v_cvt_pk_bf16_f32 v200, v14, v15
	v_exp_f32_e32 v14, v13
	v_mul_f32_e32 v13, 0x3fb8aa3b, v63
	v_exp_f32_e32 v15, v13
	v_and_b32_e32 v159, 0xffff0000, v1
	v_pk_mul_f32 v[158:159], v[158:159], s[20:21] op_sel_hi:[1,0]
	v_mul_f32_e32 v13, 0xbfb8aa3b, v62
	v_pk_mul_f32 v[14:15], v[158:159], v[14:15]
	v_lshlrev_b32_e32 v158, 16, v5
	v_cvt_pk_bf16_f32 v209, v14, v15
	v_exp_f32_e32 v14, v13
	v_mul_f32_e32 v13, 0xbfb8aa3b, v63
	v_exp_f32_e32 v15, v13
	v_sub_f32_e32 v13, v202, v62
	v_mul_f32_e32 v13, 0x3fb8aa3b, v13
	v_exp_f32_e32 v62, v13
	v_sub_f32_e32 v13, v203, v63
	v_mul_f32_e32 v13, 0x3fb8aa3b, v13
	v_exp_f32_e32 v63, v13
	v_and_b32_e32 v159, 0xffff0000, v5
	v_pk_mul_f32 v[14:15], v[14:15], v[158:159]
	v_mul_f32_e32 v13, 0x3fb8aa3b, v64
	v_cvt_pk_bf16_f32 v61, v14, v15
	v_pk_mul_f32 v[14:15], v[62:63], v[158:159]
	v_lshlrev_b32_e32 v62, 16, v2
	v_cvt_pk_bf16_f32 v201, v14, v15
	v_exp_f32_e32 v14, v13
	v_mul_f32_e32 v13, 0x3fb8aa3b, v65
	v_exp_f32_e32 v15, v13
	v_and_b32_e32 v63, 0xffff0000, v2
	v_pk_mul_f32 v[62:63], v[62:63], s[20:21] op_sel_hi:[1,0]
	v_mul_f32_e32 v13, 0xbfb8aa3b, v64
	v_pk_mul_f32 v[14:15], v[62:63], v[14:15]
	v_lshlrev_b32_e32 v158, 16, v6
	v_cvt_pk_bf16_f32 v210, v14, v15
	v_exp_f32_e32 v14, v13
	v_mul_f32_e32 v13, 0xbfb8aa3b, v65
	v_exp_f32_e32 v15, v13
	s_waitcnt lgkmcnt(0)
	v_sub_f32_e32 v13, v204, v64
	v_mul_f32_e32 v13, 0x3fb8aa3b, v13
	v_exp_f32_e32 v64, v13
	v_sub_f32_e32 v13, v205, v65
	v_mul_f32_e32 v13, 0x3fb8aa3b, v13
	v_exp_f32_e32 v65, v13
	v_and_b32_e32 v159, 0xffff0000, v6
	v_pk_mul_f32 v[14:15], v[14:15], v[158:159]
	v_mul_f32_e32 v13, 0x3fb8aa3b, v66
	v_cvt_pk_bf16_f32 v62, v14, v15
	v_pk_mul_f32 v[14:15], v[64:65], v[158:159]
	v_lshlrev_b32_e32 v64, 16, v3
	v_cvt_pk_bf16_f32 v202, v14, v15
	v_exp_f32_e32 v14, v13
	v_mul_f32_e32 v13, 0x3fb8aa3b, v67
	v_exp_f32_e32 v15, v13
	v_and_b32_e32 v65, 0xffff0000, v3
	v_pk_mul_f32 v[64:65], v[64:65], s[20:21] op_sel_hi:[1,0]
	v_mul_f32_e32 v13, 0xbfb8aa3b, v66
	v_pk_mul_f32 v[14:15], v[64:65], v[14:15]
	s_nop 0
	v_cvt_pk_bf16_f32 v211, v14, v15
	v_exp_f32_e32 v14, v13
	v_mul_f32_e32 v13, 0xbfb8aa3b, v67
	v_exp_f32_e32 v15, v13
	v_sub_f32_e32 v13, v206, v66
	v_mul_f32_e32 v13, 0x3fb8aa3b, v13
	v_exp_f32_e32 v64, v13
	v_sub_f32_e32 v13, v207, v67
	v_mul_f32_e32 v13, 0x3fb8aa3b, v13
	v_exp_f32_e32 v65, v13
	v_lshlrev_b32_e32 v66, 16, v7
	v_and_b32_e32 v67, 0xffff0000, v7
	v_pk_mul_f32 v[14:15], v[14:15], v[66:67]
	s_nop 0
	v_cvt_pk_bf16_f32 v63, v14, v15
	v_pk_mul_f32 v[14:15], v[64:65], v[66:67]
	s_nop 0
	v_cvt_pk_bf16_f32 v203, v14, v15
	ds_write_b128 v183, v[208:211] offset:38912
	ds_write_b128 v183, v[60:63] offset:52224
	ds_write_b128 v184, v[200:203]
	s_and_saveexec_b64 s[78:79], s[46:47]
	s_cbranch_execz .LBB0_492
; #define LAS __attribute__((address_space(3)))
; DI unsigned cvt_pk_bf16(float lo, float hi) { const f32x2_t v = {lo, hi}; const bf16v2_t b = __builtin_convertvector(v, bf16v2_t); return __builtin_bit_cast(unsigned, b); }
; DI float bf_lo(unsigned u) { return __uint_as_float(u << 16); }
; DI float bf_hi(unsigned u) { return __uint_as_float(u & 0xffff0000u); }
; DI void gla_item(ldsp lds, const Params& p, const bf16_t* proj, bf16_t* obuf, const float* q0k0, int jl, int item, int tid, int wid, int lane) {
;     ...
; #pragma unroll
;         for (int cc = 0; cc < 2; ++cc) {
;             if (cc == 1 && !has1) break;
;             const int row = cc ? row1 : row0, ch = cc ? ch1 : ch0;
;             const u32x4 qv = cc ? qreg1 : qreg0, kv = cc ? kreg1 : kreg0;
;             const f32x4 b0v = *(LAS f32x4*)(LA + row * SLA + ch * 8), b1v = *(LAS f32x4*)(LA + row * SLA + ch * 8 + 4);
;             const f32x4 l0v = *(LAS f32x4*)(LA + 63 * SLA + ch * 8), l1v = *(LAS f32x4*)(LA + 63 * SLA + ch * 8 + 4);
;             u32x4 qi, ki, ko;
; #pragma unroll
;             for (int e2 = 0; e2 < 4; ++e2) {
;                 const float bA = e2 < 2 ? b0v[2 * e2] : b1v[2 * e2 - 4], bB = e2 < 2 ? b0v[2 * e2 + 1] : b1v[2 * e2 - 3];
;                 const float lA = e2 < 2 ? l0v[2 * e2] : l1v[2 * e2 - 4], lB = e2 < 2 ? l0v[2 * e2 + 1] : l1v[2 * e2 - 3];
;                 const float qa = bf_lo(qv[e2]), qb = bf_hi(qv[e2]), ka = bf_lo(kv[e2]), kb = bf_hi(kv[e2]);
;                 qi[e2] = cvt_pk_bf16(qa * 0.10206207261596575f * __expf(bA), qb * 0.10206207261596575f * __expf(bB));
;                 ki[e2] = cvt_pk_bf16(ka * __expf(-bA), kb * __expf(-bB));
;                 ko[e2] = cvt_pk_bf16(ka * __expf(lA - bA), kb * __expf(lB - bB));
;             }
;             *(LAS u32x4*)(QI + row * S96 + ch * 16) = qi;
;             *(LAS u32x4*)(KI + row * S96 + ch * 16) = ki;
;             *(LAS u32x4*)(KO + row * S96 + ch * 16) = ko;
;         }
;         if (n + 1 < 32) GLA_LOAD_CHUNK(n + 1);
	ds_read_b128 v[60:63], v168 offset:13312
	ds_read_b128 v[64:67], v168 offset:13328
	ds_read_b128 v[200:203], v169 offset:38512
	ds_read_b128 v[204:207], v169 offset:38528
	v_lshlrev_b32_e32 v158, 16, v16
	s_waitcnt lgkmcnt(3)
	v_mul_f32_e32 v13, 0x3fb8aa3b, v60
	v_mul_f32_e32 v15, 0x3fb8aa3b, v61
	v_exp_f32_e32 v14, v13
	v_exp_f32_e32 v15, v15
	v_and_b32_e32 v159, 0xffff0000, v16
	v_pk_mul_f32 v[158:159], v[158:159], s[20:21] op_sel_hi:[1,0]
	v_mul_f32_e32 v13, 0xbfb8aa3b, v60
	v_pk_mul_f32 v[14:15], v[158:159], v[14:15]
	v_lshlrev_b32_e32 v160, 16, v20
	v_cvt_pk_bf16_f32 v208, v14, v15
	v_exp_f32_e32 v14, v13
	v_mul_f32_e32 v13, 0xbfb8aa3b, v61
	v_exp_f32_e32 v15, v13
	s_waitcnt lgkmcnt(1)
	v_sub_f32_e32 v13, v200, v60
	v_mul_f32_e32 v13, 0x3fb8aa3b, v13
	v_exp_f32_e32 v158, v13
	v_sub_f32_e32 v13, v201, v61
	v_mul_f32_e32 v13, 0x3fb8aa3b, v13
	v_exp_f32_e32 v159, v13
	v_and_b32_e32 v161, 0xffff0000, v20
	v_pk_mul_f32 v[14:15], v[14:15], v[160:161]
	v_mul_f32_e32 v13, 0x3fb8aa3b, v62
	v_cvt_pk_bf16_f32 v60, v14, v15
	v_pk_mul_f32 v[14:15], v[158:159], v[160:161]
	v_lshlrev_b32_e32 v158, 16, v17
	v_cvt_pk_bf16_f32 v200, v14, v15
	v_exp_f32_e32 v14, v13
	v_mul_f32_e32 v13, 0x3fb8aa3b, v63
	v_exp_f32_e32 v15, v13
	v_and_b32_e32 v159, 0xffff0000, v17
	v_pk_mul_f32 v[158:159], v[158:159], s[20:21] op_sel_hi:[1,0]
	v_mul_f32_e32 v13, 0xbfb8aa3b, v62
	v_pk_mul_f32 v[14:15], v[158:159], v[14:15]
	v_lshlrev_b32_e32 v158, 16, v21
	v_cvt_pk_bf16_f32 v209, v14, v15
	v_exp_f32_e32 v14, v13
	v_mul_f32_e32 v13, 0xbfb8aa3b, v63
	v_exp_f32_e32 v15, v13
	v_sub_f32_e32 v13, v202, v62
	v_mul_f32_e32 v13, 0x3fb8aa3b, v13
	v_exp_f32_e32 v62, v13
	v_sub_f32_e32 v13, v203, v63
	v_mul_f32_e32 v13, 0x3fb8aa3b, v13
	v_exp_f32_e32 v63, v13
	v_and_b32_e32 v159, 0xffff0000, v21
	v_pk_mul_f32 v[14:15], v[14:15], v[158:159]
	v_mul_f32_e32 v13, 0x3fb8aa3b, v64
	v_cvt_pk_bf16_f32 v61, v14, v15
	v_pk_mul_f32 v[14:15], v[62:63], v[158:159]
	v_lshlrev_b32_e32 v62, 16, v18
	v_cvt_pk_bf16_f32 v201, v14, v15
	v_exp_f32_e32 v14, v13
	v_mul_f32_e32 v13, 0x3fb8aa3b, v65
	v_exp_f32_e32 v15, v13
	v_and_b32_e32 v63, 0xffff0000, v18
	v_pk_mul_f32 v[62:63], v[62:63], s[20:21] op_sel_hi:[1,0]
	v_mul_f32_e32 v13, 0xbfb8aa3b, v64
	v_pk_mul_f32 v[14:15], v[62:63], v[14:15]
	v_lshlrev_b32_e32 v158, 16, v22
	v_cvt_pk_bf16_f32 v210, v14, v15
	v_exp_f32_e32 v14, v13
	v_mul_f32_e32 v13, 0xbfb8aa3b, v65
	v_exp_f32_e32 v15, v13
	s_waitcnt lgkmcnt(0)
	v_sub_f32_e32 v13, v204, v64
	v_mul_f32_e32 v13, 0x3fb8aa3b, v13
	v_exp_f32_e32 v64, v13
	v_sub_f32_e32 v13, v205, v65
	v_mul_f32_e32 v13, 0x3fb8aa3b, v13
	v_exp_f32_e32 v65, v13
	v_and_b32_e32 v159, 0xffff0000, v22
	v_pk_mul_f32 v[14:15], v[14:15], v[158:159]
	v_mul_f32_e32 v13, 0x3fb8aa3b, v66
	v_cvt_pk_bf16_f32 v62, v14, v15
	v_pk_mul_f32 v[14:15], v[64:65], v[158:159]
	v_lshlrev_b32_e32 v64, 16, v19
	v_cvt_pk_bf16_f32 v202, v14, v15
	v_exp_f32_e32 v14, v13
	v_mul_f32_e32 v13, 0x3fb8aa3b, v67
	v_exp_f32_e32 v15, v13
	v_and_b32_e32 v65, 0xffff0000, v19
	v_pk_mul_f32 v[64:65], v[64:65], s[20:21] op_sel_hi:[1,0]
	v_mul_f32_e32 v13, 0xbfb8aa3b, v66
	v_pk_mul_f32 v[14:15], v[64:65], v[14:15]
	s_nop 0
	v_cvt_pk_bf16_f32 v211, v14, v15
	v_exp_f32_e32 v14, v13
	v_mul_f32_e32 v13, 0xbfb8aa3b, v67
	v_exp_f32_e32 v15, v13
	v_sub_f32_e32 v13, v206, v66
	v_mul_f32_e32 v13, 0x3fb8aa3b, v13
	v_exp_f32_e32 v64, v13
	v_sub_f32_e32 v13, v207, v67
	v_mul_f32_e32 v13, 0x3fb8aa3b, v13
	v_exp_f32_e32 v65, v13
	v_lshlrev_b32_e32 v66, 16, v23
	v_and_b32_e32 v67, 0xffff0000, v23
	v_pk_mul_f32 v[14:15], v[14:15], v[66:67]
	s_nop 0
	v_cvt_pk_bf16_f32 v63, v14, v15
	v_pk_mul_f32 v[14:15], v[64:65], v[66:67]
	s_nop 0
	v_cvt_pk_bf16_f32 v203, v14, v15
	ds_write_b128 v185, v[208:211] offset:38912
	ds_write_b128 v185, v[60:63] offset:52224
	ds_write_b128 v186, v[200:203]
.LBB0_492:
	s_or_b64 exec, exec, s[78:79]
	s_cmp_eq_u32 s0, 31
	s_cbranch_scc1 .LBB0_498
	v_lshl_add_u64 v[0:1], s[6:7], 0, v[136:137]
	v_add_co_u32_e32 v4, vcc, 0x68a0000, v0
	s_nop 1
	v_addc_co_u32_e32 v5, vcc, 0, v1, vcc
	global_load_dwordx4 v[0:3], v[4:5], off
	s_nop 0
	global_load_dwordx4 v[4:7], v[4:5], off offset:768
	s_and_saveexec_b64 s[22:23], s[46:47]
	s_cbranch_execz .LBB0_495
	v_lshl_add_u64 v[14:15], s[6:7], 0, v[128:129]
	v_add_co_u32_e32 v14, vcc, 0x68a0000, v14
	s_nop 1
	v_addc_co_u32_e32 v15, vcc, 0, v15, vcc
	global_load_dwordx4 v[16:19], v[14:15], off
	global_load_dwordx4 v[20:23], v[14:15], off offset:768
